# attention staging segment: load address math and K-half LDS writes also hoisted before the first staging barrier
# speedup vs baseline: 1.0158x; 1.0080x over previous
; #define SBAR() __builtin_amdgcn_sched_barrier(0)
; #define SLOADA(k0) do { vsA0 = *(const bf16x8*)(&Vh[(size_t)((k0) + sr) * LDP + sc]); vsA1 = *(const bf16x8*)(&Vh[(size_t)((k0) + 32 + sr) * LDP + sc]); \
;     ksA0 = *(const bf16x8*)(&Kh[(size_t)((k0) + sr) * LDP + sc]); ksA1 = *(const bf16x8*)(&Kh[(size_t)((k0) + 32 + sr) * LDP + sc]); } while (0)
; #define SWRITEA(b) do { *(bf16x8*)(V_lds + (b) * SHM_V + vst0) = vsA0; *(bf16x8*)(V_lds + (b) * SHM_V + vst1) = vsA1; const int kc = sc * 2; \
;     *(bf16x8*)(K_lds + (b) * SHM_K + KSWZ(sr, kc)) = ksA0; *(bf16x8*)(K_lds + (b) * SHM_K + KSWZ(32 + sr, kc)) = ksA1; } while (0)
; #define SWAIT() asm volatile("s_waitcnt vmcnt(4)" ::: "memory")
; __device__ __forceinline__ void attn_unit(const bf16* __restrict__ P, bf16* __restrict__ MIXIN, const float* __restrict__ gn, int seq0, int h, int q0, int nt, float kmax0, float kmax1, float slope, float lam, char* lds) {
;     ...
;     __syncthreads(); SWAIT(); SWRITEA(0); __syncthreads();
;     if (j + 3 < t1) SLOADA((j + 3) * 64); SBAR();
.Lattn_i2_done:
	s_add_i32 s76, s33, 2
	s_cmp_ge_i32 s76, s3
	s_cbranch_scc1 .Lattn_nocalcA
	v_subrev_u32_e32 v214, 32, v246
	v_mad_i64_i32 v[214:215], vcc, v214, s27, 0
	v_or_b32_e32 v214, v214, v185
	v_mad_i64_i32 v[216:217], vcc, v246, s27, 0
	v_lshl_add_u64 v[214:215], v[214:215], 1, s[24:25]
	v_or_b32_e32 v216, v216, v185
	v_lshl_add_u64 v[216:217], v[216:217], 1, s[24:25]
.Lattn_nocalcA:
	s_waitcnt vmcnt(4)
	ds_write_b128 v237, v[148:151] offset:32768
	ds_write_b128 v238, v[156:159] offset:32768
	s_barrier
	s_waitcnt vmcnt(4)
	s_cmp_ge_i32 s76, s3
	s_cselect_b64 s[0:1], -1, 0
	s_and_b64 vcc, exec, s[0:1]
	ds_write_b128 v239, v[144:147]
	ds_write_b128 v240, v[152:155]
	s_waitcnt lgkmcnt(0)
	s_barrier
	s_cbranch_vccnz .LBB0_328
	global_load_dwordx4 v[144:147], v[214:215], off offset:2048
	global_load_dwordx4 v[148:151], v[214:215], off offset:1024
	global_load_dwordx4 v[152:155], v[216:217], off offset:2048
	global_load_dwordx4 v[156:159], v[216:217], off offset:1024

; #define SWRITEB(b) do { *(bf16x8*)(V_lds + (b) * SHM_V + vst0) = vsB0; *(bf16x8*)(V_lds + (b) * SHM_V + vst1) = vsB1; const int kc = sc * 2; \
;     *(bf16x8*)(K_lds + (b) * SHM_K + KSWZ(sr, kc)) = ksB0; *(bf16x8*)(K_lds + (b) * SHM_K + KSWZ(32 + sr, kc)) = ksB1; } while (0)
; #define SWAIT() asm volatile("s_waitcnt vmcnt(4)" ::: "memory")
; __device__ __forceinline__ void attn_unit(const bf16* __restrict__ P, bf16* __restrict__ MIXIN, const float* __restrict__ gn, int seq0, int h, int q0, int nt, float kmax0, float kmax1, float slope, float lam, char* lds) {
;     ...
;     __syncthreads(); SWAIT(); SWRITEB(1); __syncthreads();
;   }
.Lattn_i1_done:
	v_add_u32_e32 v246, 0x80, v246
	s_add_i32 s98, s76, 1
	s_cmp_ge_i32 s98, s3
	s_cbranch_scc1 .Lattn_nocalcB
	v_add_u32_e32 v214, 0xffffffa0, v246
	v_mad_i64_i32 v[214:215], s[98:99], v214, s27, 0
	v_subrev_u32_e32 v216, 64, v246
	v_or_b32_e32 v214, v214, v185
	v_mad_i64_i32 v[216:217], s[98:99], v216, s27, 0
	v_lshl_add_u64 v[214:215], v[214:215], 1, s[24:25]
	v_or_b32_e32 v216, v216, v185
	v_lshl_add_u64 v[216:217], v[216:217], 1, s[24:25]
.Lattn_nocalcB:
	s_waitcnt vmcnt(4)
	s_and_b64 vcc, exec, s[0:1]
	s_cbranch_vccz .Lattn_kwB
	s_waitcnt vmcnt(0)
.Lattn_kwB:
	ds_write_b128 v237, v[164:167] offset:49152
	ds_write_b128 v238, v[172:175] offset:49152
	s_barrier
	s_waitcnt vmcnt(4)
	s_and_b64 vcc, exec, s[0:1]
	s_waitcnt vmcnt(3)
	ds_write_b128 v239, v[160:163] offset:16384
	s_waitcnt vmcnt(1)
	ds_write_b128 v240, v[168:171] offset:16384
	s_waitcnt vmcnt(0)
	s_waitcnt lgkmcnt(0)
	s_barrier
	s_cbranch_vccnz .LBB0_336
	s_mov_b32 s33, s76
	s_add_i32 s0, s33, 1
	s_cmp_ge_i32 s0, s3
	s_cbranch_scc1 .LBB0_326
	global_load_dwordx4 v[160:163], v[214:215], off offset:2048
	global_load_dwordx4 v[164:167], v[214:215], off offset:1024
	global_load_dwordx4 v[168:171], v[216:217], off offset:2048
	global_load_dwordx4 v[172:175], v[216:217], off offset:1024
	s_branch .LBB0_326
